# mix phase: static s_setprio 2 for waves 0-3 to de-phase the two waves per SIMD (compute of one overlaps memory wait of the other)
# baseline (speedup 1.0000x reference)
; #define LAS __attribute__((address_space(3)))
; __device__ __forceinline__ void mix_phase(const Params& P, int l, int gw, int NGW, int lane, LAS unsigned char* lds) {
;     unsigned char* ws = P.ws;
;     bf16_t* P1 = (bf16_t*)(ws + OFF_P1); bf16_t* Q = (bf16_t*)(ws + OFF_Q); bf16_t* KF = (bf16_t*)(ws + OFF_KF); bf16_t* V = (bf16_t*)(ws + OFF_V); const bf16_t* Z = (const bf16_t*)(ws + OFF_Z);
;     const float* cs = (const float*)(ws + OFF_CS);
;     LAS float* Lq = (LAS float*)lds; LAS float* Lk = Lq + 192; LAS float* Lc = Lk + 192;
;     for (int i = threadIdx.x; i < 192; i += 512) { Lq[i] = P.q_norm[l * DQK + i]; Lk[i] = P.k_norm[l * DQK + i]; }
;     for (int i = threadIdx.x; i < 3072; i += 512) Lc[i] = P.conv_w[l * 3072 + i];
;     __syncthreads();
.LBB0_1565:
	s_andn2_b64 vcc, exec, s[0:1]
	s_cbranch_vccnz .LBB0_1611
	v_readfirstlane_b32 s2, v194
	s_nop 3
	s_cmpk_lt_u32 s2, 0x100
	s_cbranch_scc0 .Lm_prio_done
	s_setprio 2
.Lm_prio_done:
	s_mov_b64 s[0:1], exec
	v_readlane_b32 s2, v246, 5
	v_readlane_b32 s3, v246, 6
	s_and_b64 s[2:3], s[0:1], s[2:3]
	s_mov_b64 exec, s[2:3]
	s_cbranch_execz .LBB0_1568
	v_readlane_b32 s2, v246, 13
	v_readlane_b32 s3, v246, 14
	s_and_b64 s[2:3], s[2:3], exec
	s_cselect_b32 s2, 0xc0, 0
	v_readlane_b32 s52, v249, 31
	s_waitcnt vmcnt(0)
	v_add_lshl_u32 v0, s2, v194, 2
	v_readlane_b32 s54, v249, 33
	v_readlane_b32 s55, v249, 34
	v_readlane_b32 s56, v249, 35
	v_readlane_b32 s57, v249, 36
	s_nop 2
	global_load_dword v1, v0, s[54:55]
	s_nop 0
	global_load_dword v0, v0, s[56:57]
	v_readlane_b32 s53, v249, 32
	v_readlane_b32 s58, v249, 37
	v_readlane_b32 s59, v249, 38
	v_readlane_b32 s60, v249, 39
	v_readlane_b32 s61, v249, 40
	v_readlane_b32 s62, v249, 41
	v_readlane_b32 s63, v249, 42
	v_readlane_b32 s64, v249, 43
	v_readlane_b32 s65, v249, 44
	v_readlane_b32 s66, v249, 45
	v_readlane_b32 s67, v249, 46
	s_waitcnt vmcnt(0)
	ds_write2st64_b32 v195, v1, v0 offset1:3

; __device__ __forceinline__ void mix_phase(const Params& P, int l, int gw, int NGW, int lane, LAS unsigned char* lds) {
;     ...
;     __syncthreads();
.LBB0_1610:
	s_setprio 0
	s_barrier
